# grid barrier: last cross-XCD arriver releases all XCD generation words directly (one hop less per seam); P0 leftover row groups and rope entries moved to the blocks without transpose work
# speedup vs baseline: 1.0063x; 1.0062x over previous
.LBB0_91:
	s_cmp_lg_u32 s72, 0x100
	s_cbranch_scc1 .Lp0_nomap
	v_readfirstlane_b32 s4, v72
	s_lshr_b32 s4, s4, 6
	s_lshl_b32 s4, s4, 8
	s_add_i32 s5, s2, 64
	s_and_b32 s5, s5, 0xff
	s_add_i32 s14, s4, s5

.LBB0_96:
	s_sub_i32 s4, 0xff, s2
	s_cmp_eq_u32 s72, 0x100
	s_cselect_b32 s4, s4, s2
	v_lshl_add_u32 v12, s4, 9, v72
	s_mov_b32 s4, 0x10200
	v_cmp_gt_i32_e32 vcc, s4, v12
	s_and_saveexec_b64 s[6:7], vcc
	s_cbranch_execz .LBB0_101
	v_and_b32_e32 v13, 15, v72
	s_mov_b32 s4, 0x979a371
	v_cvt_f64_u32_e32 v[2:3], v13
	s_mov_b32 s5, 0xbfea934f
	v_mul_f64 v[2:3], v[2:3], s[4:5]
	v_rndne_f64_e32 v[4:5], v[2:3]
	s_mov_b32 s4, 0x3b39803f
	v_add_f64 v[6:7], v[2:3], -v[4:5]
	s_mov_b32 s5, 0x3c7abc9e
	v_mul_f64 v[8:9], v[6:7], s[4:5]
	s_mov_b32 s4, 0xfefa39ef
	s_mov_b32 s5, 0x3fe62e42
	v_fmac_f64_e32 v[8:9], s[4:5], v[6:7]
	s_mov_b32 s4, 0x6a5dcb37
	v_mov_b32_e32 v6, 0xfca7ab0c
	v_mov_b32_e32 v7, 0x3e928af3
	s_mov_b32 s5, 0x3e5ade15
	v_fmac_f64_e32 v[6:7], s[4:5], v[8:9]
	v_mov_b32_e32 v10, 0x623fde64
	v_mov_b32_e32 v11, 0x3ec71dee
	v_fmac_f64_e32 v[10:11], v[8:9], v[6:7]
	v_mov_b32_e32 v6, 0x7c89e6b0
	v_mov_b32_e32 v7, 0x3efa0199
	v_fmac_f64_e32 v[6:7], v[8:9], v[10:11]
	v_mov_b32_e32 v10, 0x14761f6e
	v_mov_b32_e32 v11, 0x3f2a01a0
	v_fmac_f64_e32 v[10:11], v[8:9], v[6:7]
	v_mov_b32_e32 v6, 0x1852b7b0
	v_mov_b32_e32 v7, 0x3f56c16c
	v_fmac_f64_e32 v[6:7], v[8:9], v[10:11]
	v_mov_b32_e32 v10, 0x11122322
	v_mov_b32_e32 v11, 0x3f811111
	v_fmac_f64_e32 v[10:11], v[8:9], v[6:7]
	v_mov_b32_e32 v6, 0x555502a1
	v_mov_b32_e32 v7, 0x3fa55555
	v_fmac_f64_e32 v[6:7], v[8:9], v[10:11]
	v_mov_b32_e32 v10, 0x55555511
	v_mov_b32_e32 v11, 0x3fc55555
	v_fmac_f64_e32 v[10:11], v[8:9], v[6:7]
	v_mov_b32_e32 v6, 11
	v_mov_b32_e32 v7, 0x3fe00000
	s_mov_b32 s4, 0
	v_fmac_f64_e32 v[6:7], v[8:9], v[10:11]
	s_mov_b32 s5, 0x40900000
	v_fma_f64 v[6:7], v[8:9], v[6:7], 1.0
	v_cmp_nlt_f64_e32 vcc, s[4:5], v[2:3]
	s_mov_b32 s4, 0
	v_fma_f64 v[6:7], v[8:9], v[6:7], 1.0
	v_cvt_i32_f64_e32 v4, v[4:5]
	s_mov_b32 s5, 0xc090cc00
	v_ldexp_f64 v[4:5], v[6:7], v4
	v_mov_b32_e32 v6, 0x7ff00000
	v_cmp_ngt_f64_e64 s[4:5], s[4:5], v[2:3]
	v_cndmask_b32_e32 v5, v6, v5, vcc
	s_and_b64 vcc, s[4:5], vcc
	s_mov_b32 s14, 0x54442d18
	s_lshl_b32 s18, s72, 9
	v_cndmask_b32_e64 v3, 0, v5, s[4:5]
	v_cndmask_b32_e32 v2, 0, v4, vcc
	s_mov_b64 s[12:13], 0
	s_mov_b32 s15, 0x401921fb
	s_mov_b32 s17, 0xc01921fb
	s_mov_b32 s16, s14
	s_mov_b32 s19, 0x101ff

.LBB0_139:
	s_or_b64 exec, exec, s[14:15]
	v_cvt_f32_u32_e32 v5, v2
	s_waitcnt vmcnt(0)
	v_readfirstlane_b32 s12, v4
	s_add_u32 s14, s66, 0x4500
	s_addc_u32 s15, s67, 0
	v_rcp_iflag_f32_e32 v5, v5
	v_add_u32_e32 v3, s12, v3
	v_add_u32_e32 v6, 1, v3
	s_mov_b64 s[16:17], -1
	v_mul_f32_e32 v4, 0x4f7ffffe, v5
	v_cvt_u32_f32_e32 v4, v4
	v_sub_u32_e32 v5, 0, v2
	v_mul_lo_u32 v5, v5, v4
	v_mul_hi_u32 v5, v4, v5
	v_add_u32_e32 v4, v4, v5
	v_mul_hi_u32 v4, v3, v4
	v_mul_lo_u32 v5, v4, v2
	v_sub_u32_e32 v3, v3, v5
	v_add_u32_e32 v7, 1, v4
	v_cmp_ge_u32_e32 vcc, v3, v2
	v_sub_u32_e32 v5, v3, v2
	s_nop 0
	v_cndmask_b32_e32 v4, v4, v7, vcc
	v_cndmask_b32_e32 v3, v3, v5, vcc
	v_add_u32_e32 v5, 1, v4
	v_cmp_ge_u32_e32 vcc, v3, v2
	s_nop 1
	v_cndmask_b32_e32 v4, v4, v5, vcc
	v_mul_lo_u32 v3, v2, v4
	v_add_u32_e32 v2, v3, v2
	v_cmp_ne_u32_e32 vcc, v6, v2
	s_cbranch_vccnz .Lxr_skip_0
	v_mov_b32_e32 v5, 0x3400
	v_mov_b32_e32 v7, 1
	global_atomic_add v5, v7, s[66:67]
	global_atomic_add v5, v7, s[66:67] offset:256
	global_atomic_add v5, v7, s[66:67] offset:512
	global_atomic_add v5, v7, s[66:67] offset:768
	global_atomic_add v5, v7, s[66:67] offset:1024
	global_atomic_add v5, v7, s[66:67] offset:1280
	global_atomic_add v5, v7, s[66:67] offset:1536
	global_atomic_add v5, v7, s[66:67] offset:1792
	global_atomic_add v5, v7, s[66:67] offset:2048
	global_atomic_add v5, v7, s[66:67] offset:2304
	global_atomic_add v5, v7, s[66:67] offset:2560
	global_atomic_add v5, v7, s[66:67] offset:2816
	global_atomic_add v5, v7, s[66:67] offset:3072
	global_atomic_add v5, v7, s[66:67] offset:3328
	global_atomic_add v5, v7, s[66:67] offset:3584
	global_atomic_add v5, v7, s[66:67] offset:3840
.Lxr_skip_0:
	v_mov_b64_e32 v[2:3], s[14:15]
	s_and_saveexec_b64 s[12:13], vcc
	s_cbranch_execz .LBB0_151
	v_mov_b32_e32 v2, 0
	global_load_dword v3, v2, s[14:15] sc1
	s_mov_b64 s[20:21], 0
	s_waitcnt vmcnt(0)
	v_cmp_eq_u32_e32 vcc, v3, v4
	s_and_saveexec_b64 s[18:19], vcc
	s_cbranch_execz .LBB0_150
	s_add_u32 s16, s66, 0x1200
	s_addc_u32 s17, s67, 0
	s_mov_b32 s28, 1
	s_branch .LBB0_143

.LBB0_153:
	s_or_b64 exec, exec, s[12:13]
	s_mov_b64 s[12:13], exec
	v_mbcnt_lo_u32_b32 v2, s12, 0
	v_mbcnt_hi_u32_b32 v2, s13, v2
	v_cmp_eq_u32_e32 vcc, 0, v2
	s_waitcnt vmcnt(0)
	buffer_inv sc1
	s_and_saveexec_b64 s[14:15], vcc
	s_cbranch_execz .LBB0_155
	s_bcnt1_i32_b64 s12, s[12:13]
	v_mov_b32_e32 v2, 0x2000
	v_mov_b32_e32 v3, s12
.LBB0_155:
	s_or_b64 exec, exec, s[14:15]
	s_waitcnt vmcnt(0)

.LBB0_460:
	s_or_b64 exec, exec, s[10:11]
	v_cvt_f32_u32_e32 v5, v2
	s_waitcnt vmcnt(0)
	v_readfirstlane_b32 s8, v4
	s_add_u32 s10, s66, 0x4500
	s_addc_u32 s11, s67, 0
	v_rcp_iflag_f32_e32 v5, v5
	v_add_u32_e32 v3, s8, v3
	v_add_u32_e32 v6, 1, v3
	s_mov_b64 s[12:13], -1
	v_mul_f32_e32 v4, 0x4f7ffffe, v5
	v_cvt_u32_f32_e32 v4, v4
	v_sub_u32_e32 v5, 0, v2
	v_mul_lo_u32 v5, v5, v4
	v_mul_hi_u32 v5, v4, v5
	v_add_u32_e32 v4, v4, v5
	v_mul_hi_u32 v4, v3, v4
	v_mul_lo_u32 v5, v4, v2
	v_sub_u32_e32 v3, v3, v5
	v_add_u32_e32 v7, 1, v4
	v_cmp_ge_u32_e32 vcc, v3, v2
	v_sub_u32_e32 v5, v3, v2
	s_nop 0
	v_cndmask_b32_e32 v4, v4, v7, vcc
	v_cndmask_b32_e32 v3, v3, v5, vcc
	v_add_u32_e32 v5, 1, v4
	v_cmp_ge_u32_e32 vcc, v3, v2
	s_nop 1
	v_cndmask_b32_e32 v4, v4, v5, vcc
	v_mul_lo_u32 v3, v2, v4
	v_add_u32_e32 v2, v3, v2
	v_cmp_ne_u32_e32 vcc, v6, v2
	s_cbranch_vccnz .Lxr_skip_1
	v_mov_b32_e32 v5, 0x3400
	v_mov_b32_e32 v7, 1
	global_atomic_add v5, v7, s[66:67]
	global_atomic_add v5, v7, s[66:67] offset:256
	global_atomic_add v5, v7, s[66:67] offset:512
	global_atomic_add v5, v7, s[66:67] offset:768
	global_atomic_add v5, v7, s[66:67] offset:1024
	global_atomic_add v5, v7, s[66:67] offset:1280
	global_atomic_add v5, v7, s[66:67] offset:1536
	global_atomic_add v5, v7, s[66:67] offset:1792
	global_atomic_add v5, v7, s[66:67] offset:2048
	global_atomic_add v5, v7, s[66:67] offset:2304
	global_atomic_add v5, v7, s[66:67] offset:2560
	global_atomic_add v5, v7, s[66:67] offset:2816
	global_atomic_add v5, v7, s[66:67] offset:3072
	global_atomic_add v5, v7, s[66:67] offset:3328
	global_atomic_add v5, v7, s[66:67] offset:3584
	global_atomic_add v5, v7, s[66:67] offset:3840
.Lxr_skip_1:
	v_mov_b64_e32 v[2:3], s[10:11]
	s_and_saveexec_b64 s[8:9], vcc
	s_cbranch_execz .LBB0_472
	v_mov_b32_e32 v2, 0
	global_load_dword v3, v2, s[10:11] sc1
	s_mov_b64 s[16:17], 0
	s_waitcnt vmcnt(0)
	v_cmp_eq_u32_e32 vcc, v3, v4
	s_and_saveexec_b64 s[14:15], vcc
	s_cbranch_execz .LBB0_471
	s_add_u32 s12, s66, 0x1200
	s_addc_u32 s13, s67, 0
	s_mov_b32 s26, 1
	s_branch .LBB0_464

.LBB0_474:
	s_or_b64 exec, exec, s[8:9]
	s_mov_b64 s[8:9], exec
	v_mbcnt_lo_u32_b32 v2, s8, 0
	v_mbcnt_hi_u32_b32 v2, s9, v2
	v_cmp_eq_u32_e32 vcc, 0, v2
	s_waitcnt vmcnt(0)
	buffer_inv sc1
	s_and_saveexec_b64 s[10:11], vcc
	s_cbranch_execz .LBB0_476
	s_bcnt1_i32_b64 s8, s[8:9]
	v_mov_b32_e32 v2, 0x2000
	v_mov_b32_e32 v3, s8
.LBB0_476:
	s_or_b64 exec, exec, s[10:11]
	s_waitcnt vmcnt(0)

.LBB0_546:
	s_or_b64 exec, exec, s[8:9]
	s_mov_b64 s[8:9], exec
	v_mbcnt_lo_u32_b32 v2, s8, 0
	v_mbcnt_hi_u32_b32 v2, s9, v2
	v_cmp_eq_u32_e32 vcc, 0, v2
	s_waitcnt vmcnt(0)
	buffer_inv sc1
	s_and_saveexec_b64 s[10:11], vcc
	s_cbranch_execz .LBB0_548
	s_bcnt1_i32_b64 s8, s[8:9]
	v_mov_b32_e32 v2, 0x2000
	v_mov_b32_e32 v3, s8
.LBB0_548:
	s_or_b64 exec, exec, s[10:11]
	s_waitcnt vmcnt(0)

.Lxr_skip_3:
	v_mov_b64_e32 v[2:3], s[10:11]
	s_and_saveexec_b64 s[8:9], vcc
	s_cbranch_execz .LBB0_737
	v_mov_b32_e32 v2, 0
	global_load_dword v3, v2, s[10:11] sc1
	s_mov_b64 s[16:17], 0
	s_waitcnt vmcnt(0)
	v_cmp_eq_u32_e32 vcc, v3, v4
	s_and_saveexec_b64 s[14:15], vcc
	s_cbranch_execz .LBB0_736
	s_add_u32 s12, s66, 0x1200
	s_addc_u32 s13, s67, 0
	s_mov_b32 s28, 1
	s_branch .LBB0_729

.LBB0_739:
	s_or_b64 exec, exec, s[8:9]
	s_mov_b64 s[8:9], exec
	v_mbcnt_lo_u32_b32 v2, s8, 0
	v_mbcnt_hi_u32_b32 v2, s9, v2
	v_cmp_eq_u32_e32 vcc, 0, v2
	s_waitcnt vmcnt(0)
	buffer_inv sc1
	s_and_saveexec_b64 s[10:11], vcc
	s_cbranch_execz .LBB0_741
	s_bcnt1_i32_b64 s8, s[8:9]
	v_mov_b32_e32 v2, 0x2000
	v_mov_b32_e32 v3, s8
.LBB0_741:
	s_or_b64 exec, exec, s[10:11]
	s_waitcnt vmcnt(0)

.LBB0_1187:
	s_or_b64 exec, exec, s[8:9]
	s_mov_b64 s[8:9], exec
	v_mbcnt_lo_u32_b32 v2, s8, 0
	v_mbcnt_hi_u32_b32 v2, s9, v2
	v_cmp_eq_u32_e32 vcc, 0, v2
	s_waitcnt vmcnt(0)
	buffer_inv sc1
	s_and_saveexec_b64 s[10:11], vcc
	s_cbranch_execz .LBB0_1189
	s_bcnt1_i32_b64 s8, s[8:9]
	v_mov_b32_e32 v2, 0x2000
	v_mov_b32_e32 v3, s8
.LBB0_1189:
	s_or_b64 exec, exec, s[10:11]
	s_waitcnt vmcnt(0)

.LBB0_1303:
	s_or_b64 exec, exec, s[8:9]
	s_mov_b64 s[8:9], exec
	v_mbcnt_lo_u32_b32 v2, s8, 0
	v_mbcnt_hi_u32_b32 v2, s9, v2
	v_cmp_eq_u32_e32 vcc, 0, v2
	s_waitcnt vmcnt(0)
	buffer_inv sc1
	s_and_saveexec_b64 s[10:11], vcc
	s_cbranch_execz .LBB0_1305
	s_bcnt1_i32_b64 s8, s[8:9]
	v_mov_b32_e32 v2, 0x2000
	v_mov_b32_e32 v3, s8
.LBB0_1305:
	s_or_b64 exec, exec, s[10:11]
	s_waitcnt vmcnt(0)
